# intra-loop code placement: second step of the MLA loop (and code after it) shifted by 4 bytes, first step kept (on v37)
# baseline (speedup 1.0000x reference)
.LBB0_244:
	s_nop 0
	s_waitcnt vmcnt(5) lgkmcnt(0)
	s_barrier
	s_add_i32 s5, s20, 0
	v_add_u32_e32 v83, s5, v230
	v_add_u32_e32 v88, s5, v232
	ds_read_b128 v[84:87], v83 offset:49152
	ds_read_b128 v[186:189], v88 offset:57344
	v_add_u32_e32 v83, s5, v231
	v_add_u32_e32 v88, s5, v233
	ds_read_b128 v[190:193], v83 offset:49152
	ds_read_b128 v[210:213], v88 offset:57344
	s_waitcnt lgkmcnt(3)
	v_mfma_f32_32x32x16_bf16 v[114:129], v[84:87], v[130:133], v[66:81]
	v_add_u32_e32 v220, s5, v204
	v_add_u32_e32 v83, v220, v227
	ds_read_b128 v[236:239], v83 offset:49152
	v_lshl_add_u32 v234, s77, 13, v206
	v_add_u32_e32 v235, s13, v202
	v_exp_f32_e32 v244, v98
	ds_read_b128 v[240:243], v83 offset:57344
	v_add_f32_e32 v98, v244, v82
	s_waitcnt lgkmcnt(4)
	v_mfma_f32_32x32x16_bf16 v[82:97], v[186:189], v[130:133], v[66:81]
	v_exp_f32_e32 v245, v99
	s_waitcnt lgkmcnt(3)
	v_mfma_f32_32x32x16_bf16 v[114:129], v[190:193], v[134:137], v[114:129]
	v_add_u32_e32 v99, v220, v226
	ds_read_b128 v[186:189], v99 offset:49152
	v_add_f32_e32 v98, v245, v98
	v_exp_f32_e32 v246, v100
	s_waitcnt lgkmcnt(3)
	v_mfma_f32_32x32x16_bf16 v[82:97], v[210:213], v[134:137], v[82:97]
	ds_read_b128 v[190:193], v99 offset:57344
	v_add_f32_e32 v248, v246, v98
	v_exp_f32_e32 v247, v101
	s_waitcnt lgkmcnt(3)
	v_mfma_f32_32x32x16_bf16 v[114:129], v[236:239], v[138:141], v[114:129]
	v_add_u32_e32 v210, v220, v225
	ds_read_b128 v[98:101], v210 offset:49152
	v_exp_f32_e32 v249, v102
	v_add_f32_e32 v102, v247, v248
	s_waitcnt lgkmcnt(3)
	v_mfma_f32_32x32x16_bf16 v[82:97], v[240:243], v[138:141], v[82:97]
	ds_read_b128 v[210:213], v210 offset:57344
	v_add_f32_e32 v102, v249, v102
	v_exp_f32_e32 v248, v103
	s_waitcnt lgkmcnt(3)
	v_mfma_f32_32x32x16_bf16 v[114:129], v[186:189], v[142:145], v[114:129]
	v_add_u32_e32 v103, v220, v224
	ds_read_b128 v[236:239], v103 offset:49152
	v_add_f32_e32 v102, v248, v102
	v_exp_f32_e32 v240, v104
	s_waitcnt lgkmcnt(3)
	v_mfma_f32_32x32x16_bf16 v[82:97], v[190:193], v[142:145], v[82:97]
	ds_read_b128 v[186:189], v103 offset:57344
	v_add_f32_e32 v242, v240, v102
	v_exp_f32_e32 v241, v105
	s_waitcnt lgkmcnt(3)
	v_mfma_f32_32x32x16_bf16 v[114:129], v[98:101], v[154:157], v[114:129]
	v_add_u32_e32 v190, v220, v223
	ds_read_b128 v[102:105], v190 offset:49152
	v_add_f32_e32 v98, v241, v242
	v_exp_f32_e32 v243, v106
	s_waitcnt lgkmcnt(3)
	v_mfma_f32_32x32x16_bf16 v[82:97], v[210:213], v[154:157], v[82:97]
	ds_read_b128 v[190:193], v190 offset:57344
	v_add_f32_e32 v100, v243, v98
	v_exp_f32_e32 v242, v107
	v_cvt_pk_bf16_f32 v98, v244, v245
	v_cvt_pk_bf16_f32 v99, v246, v247
	s_waitcnt lgkmcnt(3)
	v_mfma_f32_32x32x16_bf16 v[114:129], v[236:239], v[150:153], v[114:129]
	v_add_u32_e32 v106, v220, v222
	ds_read_b128 v[210:213], v106 offset:49152
	v_add_f32_e32 v107, v242, v100
	v_exp_f32_e32 v220, v108
	v_cvt_pk_bf16_f32 v100, v249, v248
	v_cvt_pk_bf16_f32 v101, v240, v241
	s_waitcnt lgkmcnt(3)
	v_mfma_f32_32x32x16_bf16 v[82:97], v[186:189], v[150:153], v[82:97]
	ds_read_b128 v[236:239], v106 offset:57344
	v_add_f32_e32 v241, v220, v107
	v_permlane32_swap_b32_e32 v98, v100
	v_permlane32_swap_b32_e32 v99, v101
	v_exp_f32_e32 v240, v109
	s_waitcnt lgkmcnt(3)
	v_mfma_f32_32x32x16_bf16 v[114:129], v[102:105], v[146:149], v[114:129]
	v_add_u32_e32 v186, v234, v221
	ds_read_b128 v[106:109], v186
	v_exp_f32_e32 v244, v110
	v_add_f32_e32 v110, v240, v241
	s_waitcnt lgkmcnt(3)
	v_mfma_f32_32x32x16_bf16 v[82:97], v[190:193], v[146:149], v[82:97]
	ds_read_b128 v[102:105], v186 offset:4096
	v_add_f32_e32 v110, v244, v110
	v_exp_f32_e32 v241, v111
	s_waitcnt lgkmcnt(3)
	v_mfma_f32_32x32x16_bf16 v[114:129], v[210:213], v[158:161], v[114:129]
	v_add_u32_e32 v111, v234, v209
	ds_read_b128 v[186:189], v111
	v_add_f32_e32 v110, v241, v110
	v_exp_f32_e32 v245, v112
	s_waitcnt lgkmcnt(3)
	v_mfma_f32_32x32x16_bf16 v[82:97], v[236:239], v[158:161], v[82:97]
	ds_read_b128 v[190:193], v111 offset:4096
	v_add_f32_e32 v210, v245, v110
	v_exp_f32_e32 v246, v113
	s_waitcnt lgkmcnt(3)
	v_mfma_f32_32x32x16_bf16 v[114:129], v[106:109], v[162:165], v[114:129]
	v_add_u32_e32 v211, v234, v208
	ds_read_b128 v[110:113], v211
	v_add_f32_e32 v236, v246, v210
	s_waitcnt lgkmcnt(3)
	v_mfma_f32_32x32x16_bf16 v[82:97], v[102:105], v[162:165], v[82:97]
	ds_read_b128 v[106:109], v211 offset:4096
	v_cvt_pk_bf16_f32 v102, v243, v242
	v_cvt_pk_bf16_f32 v103, v220, v240
	s_waitcnt lgkmcnt(3)
	v_mfma_f32_32x32x16_bf16 v[114:129], v[186:189], v[166:169], v[114:129]
	v_add_u32_e32 v220, v234, v207
	ds_read_b128 v[210:213], v220
	v_cvt_pk_bf16_f32 v104, v244, v241
	v_cvt_pk_bf16_f32 v105, v245, v246
	s_waitcnt lgkmcnt(3)
	v_mfma_f32_32x32x16_bf16 v[82:97], v[190:193], v[166:169], v[82:97]
	ds_read_b128 v[186:189], v220 offset:4096
	v_permlane32_swap_b32_e32 v102, v104
	v_permlane32_swap_b32_e32 v103, v105
	s_waitcnt lgkmcnt(3)
	v_mfma_f32_32x32x16_bf16 v[114:129], v[110:113], v[170:173], v[114:129]
	v_mov_b32_e32 v110, v236
	s_nop 1
	v_permlane32_swap_b32_e32 v236, v110
	v_add_f32_e32 v110, v236, v110
	v_add_f32_e32 v234, v1, v110
	s_waitcnt lgkmcnt(2)
	v_mfma_f32_32x32x16_bf16 v[82:97], v[106:109], v[170:173], v[82:97]
	ds_read_b64_tr_b16 v[110:111], v235
	ds_read_b64_tr_b16 v[112:113], v235 offset:2048
	s_waitcnt lgkmcnt(3)
	v_mfma_f32_32x32x16_bf16 v[114:129], v[210:213], v[174:177], v[114:129]
	ds_read_b64_tr_b16 v[236:237], v235 offset:512
	ds_read_b64_tr_b16 v[238:239], v235 offset:2560
	s_waitcnt lgkmcnt(4)
	v_mfma_f32_32x32x16_bf16 v[82:97], v[186:189], v[174:177], v[82:97]
	ds_read_b64_tr_b16 v[106:107], v235 offset:1024
	ds_read_b64_tr_b16 v[108:109], v235 offset:3072
	s_waitcnt lgkmcnt(4)
	v_mfma_f32_32x32x16_bf16 v[50:65], v[182:185], v[110:113], v[50:65]
	s_cmpk_lt_u32 s78, 0x7c
	s_cselect_b64 s[6:7], -1, 0
	s_add_i32 s8, s13, s76
	ds_read_b64_tr_b16 v[190:191], v235 offset:1536
	ds_read_b64_tr_b16 v[192:193], v235 offset:3584
	s_add_u32 s12, s18, 0x15018100
	s_addc_u32 s13, s19, 0
	s_add_i32 s1, s1, s73
	s_mov_b32 m0, s1
	s_nop 0
	global_load_lds_dwordx4 v199, s[12:13]
	s_add_u32 s18, s18, 0x1501c100
	s_addc_u32 s19, s19, 0
	s_add_i32 s5, s1, 0x2000
	s_cmpk_gt_u32 s78, 0x7b
	s_waitcnt lgkmcnt(4)
	v_mfma_f32_32x32x16_bf16 v[34:49], v[182:185], v[236:239], v[34:49]
	ds_read_b64_tr_b16 v[186:187], v235 offset:4096
	ds_read_b64_tr_b16 v[188:189], v235 offset:6144
	s_mov_b32 m0, s5
	s_nop 0
	global_load_lds_dwordx4 v199, s[18:19]
	ds_read_b64_tr_b16 v[110:111], v235 offset:4608
	ds_read_b64_tr_b16 v[112:113], v235 offset:6656
	s_cbranch_scc1 .LBB0_246
	s_add_u32 s12, s14, 0x20000
	s_addc_u32 s13, s15, 0
	s_mov_b32 m0, s8
	s_nop 0
	global_load_lds_dwordx4 v197, s[12:13]
